# v145 + SSD conv wave-uniform fast path around the per-tap t<0 exec-mask blocks
# baseline (speedup 1.0000x reference)
.Lssd_join2:
	v_lshlrev_b64 v[52:53], 2, v[52:53]
	v_add_u32_e32 v233, 0x8000, v52
	ds_read_b128 v[114:117], v233 offset:49168
	ds_read_b128 v[122:125], v233 offset:49152
	ds_read_b128 v[126:129], v233 offset:16
	ds_read_b128 v[130:133], v233
	s_mov_b64 s[38:39], 0x3000
	ds_read_b128 v[134:137], v233 offset:12288
	s_nop 0
	ds_read_b128 v[138:141], v233 offset:12304
	s_movk_i32 s4, 0x6000
	s_mov_b64 s[40:41], 0x6000
	s_mov_b64 s[48:49], 0x9000
	s_mov_b32 s5, 0x9000
	s_cmp_lt_i32 s20, 40
	s_waitcnt lgkmcnt(2)
	s_waitcnt lgkmcnt(1)
	v_mov_b32_e32 v119, v134
	v_mov_b32_e32 v134, v131
	v_fma_f32 v0, v130, v38, v122
	v_fma_f32 v0, v119, v39, v0
	s_waitcnt lgkmcnt(0)
	v_mov_b32_e32 v38, v138
	v_mov_b32_e32 v39, v126
	v_mov_b32_e32 v126, v139
	v_fma_f32 v39, v39, v103, v114
	v_fma_f32 v11, v127, v11, v115
	v_fma_f32 v118, v38, v102, v39
	v_pk_mul_f32 v[38:39], v[134:135], v[106:107]
	v_fma_f32 v107, v139, v10, v11
	v_mov_b32_e32 v10, v132
	v_mov_b32_e32 v11, v136
	v_mov_b32_e32 v136, v133
	v_fma_f32 v10, v10, v40, v124
	v_fma_f32 v119, v11, v41, v10
	v_mov_b32_e32 v10, v140
	v_mov_b32_e32 v11, v128
	v_mov_b32_e32 v128, v141
	v_fma_f32 v11, v11, v99, v116
	v_fma_f32 v122, v10, v98, v11
	v_add_f32_e32 v38, v123, v38
	v_fma_f32 v10, v133, v100, v125
	v_fma_f32 v123, v137, v101, v10
	v_add_f32_e32 v106, v38, v39
	v_fma_f32 v11, v129, v13, v117
	v_fma_f32 v124, v141, v12, v11
	s_nop 0
	ds_read_b128 v[10:13], v233 offset:24576
	s_nop 0
	ds_read_b128 v[38:41], v233 offset:24592
	ds_read_b128 v[98:101], v233 offset:36864
	ds_read_b128 v[114:117], v233 offset:36880
	s_waitcnt lgkmcnt(3)
	s_waitcnt lgkmcnt(1)
	v_mov_b32_e32 v53, v98
	v_mov_b32_e32 v98, v11
	v_fma_f32 v0, v10, v46, v0
	v_fma_f32 v0, v53, v47, v0
	s_waitcnt lgkmcnt(0)
	v_mov_b32_e32 v46, v114
	v_mov_b32_e32 v47, v38
	v_fma_f32 v10, v47, v111, v118
	v_fma_f32 v46, v46, v110, v10
	s_nop 0
	v_fma_f32 v10, v98, v112, v106
	v_fma_f32 v47, v99, v113, v10
	s_nop 0
	v_fma_f32 v11, v39, v43, v107
	v_fma_f32 v38, v115, v42, v11
	v_mov_b32_e32 v10, v12
	v_mov_b32_e32 v11, v100
	v_fma_f32 v10, v10, v48, v119
	v_fma_f32 v12, v11, v49, v10
	v_mov_b32_e32 v10, v116
	v_mov_b32_e32 v11, v40
	v_mov_b32_e32 v40, v117
	v_fma_f32 v11, v11, v105, v122
	v_fma_f32 v39, v10, v104, v11
	s_nop 0
	v_fma_f32 v10, v13, v108, v123
	v_fma_f32 v13, v101, v109, v10
	v_pk_mul_f32 v[10:11], v[40:41], v[44:45]
	v_mul_f32_e32 v40, 0xbfb8aa3b, v12
	v_exp_f32_e32 v40, v40
	v_mul_f32_e32 v41, 0xbfb8aa3b, v38
	v_exp_f32_e32 v41, v41
	v_add_f32_e32 v11, v11, v124
	v_add_f32_e32 v40, 1.0, v40
	v_rcp_f32_e32 v40, v40
	v_add_f32_e32 v41, 1.0, v41
	v_rcp_f32_e32 v41, v41
	v_add_f32_e32 v10, v10, v11
	v_mul_f32_e32 v11, 0xbfb8aa3b, v0
	v_mul_f32_e32 v12, v12, v40
	v_mul_f32_e32 v40, 0xbfb8aa3b, v13
	v_exp_f32_e32 v11, v11
	v_exp_f32_e32 v40, v40
	v_mul_f32_e32 v38, v38, v41
	v_mul_f32_e32 v41, 0xbfb8aa3b, v39
	v_exp_f32_e32 v41, v41
	v_add_f32_e32 v11, 1.0, v11
	v_add_f32_e32 v40, 1.0, v40
	v_rcp_f32_e32 v11, v11
	v_rcp_f32_e32 v40, v40
	v_add_f32_e32 v41, 1.0, v41
	v_rcp_f32_e32 v41, v41
	v_mul_f32_e32 v0, v0, v11
	v_mul_f32_e32 v11, 0xbfb8aa3b, v47
	v_mul_f32_e32 v13, v13, v40
	v_mul_f32_e32 v40, 0xbfb8aa3b, v46
	v_exp_f32_e32 v11, v11
	v_exp_f32_e32 v40, v40
	v_mul_f32_e32 v39, v39, v41
	v_mul_f32_e32 v41, 0xbfb8aa3b, v10
	v_exp_f32_e32 v41, v41
	v_add_f32_e32 v11, 1.0, v11
	v_add_f32_e32 v40, 1.0, v40
	v_rcp_f32_e32 v11, v11
	v_rcp_f32_e32 v40, v40
	v_add_f32_e32 v41, 1.0, v41
	v_rcp_f32_e32 v41, v41
	v_mul_f32_e32 v11, v47, v11
	v_mul_f32_e32 v40, v46, v40
	v_lshlrev_b64 v[46:47], 2, v[50:51]
	v_add_u32_e32 v233, 0x8000, v46
	v_lshl_add_u64 v[98:99], s[8:9], 0, v[46:47]
	v_mul_f32_e32 v41, v10, v41
	v_cvt_pk_bf16_f32 v10, v0, v11
	v_cvt_pk_bf16_f32 v11, v12, v13
	v_cvt_pk_bf16_f32 v12, v40, v38
	v_cvt_pk_bf16_f32 v13, v39, v41
	ds_read_b128 v[38:41], v233 offset:49168
	s_nop 0
	ds_read_b128 v[42:45], v233 offset:49152
	s_nop 0
	ds_read_b128 v[46:49], v233 offset:16
	ds_read_b128 v[50:53], v233
	ds_read_b128 v[102:105], v233 offset:12288
	s_nop 0
	ds_read_b128 v[106:109], v233 offset:12304
	s_waitcnt lgkmcnt(2)
	s_waitcnt lgkmcnt(1)
	v_mov_b32_e32 v101, v102
	v_mov_b32_e32 v102, v51
	v_fma_f32 v0, v50, v34, v42
	v_fma_f32 v100, v101, v35, v0
	s_waitcnt lgkmcnt(0)
	v_mov_b32_e32 v34, v106
	v_mov_b32_e32 v35, v46
	v_fma_f32 v0, v35, v95, v38
	v_fma_f32 v94, v34, v94, v0
	v_fma_f32 v0, v51, v96, v43
	v_fma_f32 v51, v103, v97, v0
	v_fma_f32 v0, v47, v31, v39
	v_fma_f32 v50, v107, v30, v0
	v_mov_b32_e32 v30, v52
	v_mov_b32_e32 v31, v104
	v_mov_b32_e32 v104, v53
	v_fma_f32 v0, v30, v36, v44
	v_fma_f32 v0, v31, v37, v0
	v_mov_b32_e32 v30, v108
	v_mov_b32_e32 v31, v48
	v_fma_f32 v31, v31, v91, v40
	v_fma_f32 v46, v30, v90, v31
	v_fma_f32 v30, v53, v92, v45
	v_fma_f32 v47, v105, v93, v30
	v_fma_f32 v31, v49, v33, v41
	s_nop 0
	v_fma_f32 v48, v109, v32, v31
	ds_read_b128 v[34:37], v233 offset:24576
	s_nop 0
	ds_read_b128 v[30:33], v233 offset:24592
	s_nop 0
	ds_read_b128 v[38:41], v233 offset:36864
	s_nop 0
	ds_read_b128 v[42:45], v233 offset:36880
	s_waitcnt lgkmcnt(3)
	v_mov_b32_e32 v52, v34
	s_waitcnt lgkmcnt(1)
	v_mov_b32_e32 v53, v38
	v_fma_f32 v26, v34, v26, v100
	v_fma_f32 v34, v53, v27, v26
	s_waitcnt lgkmcnt(0)
	v_mov_b32_e32 v26, v42
	v_mov_b32_e32 v27, v30
	v_fma_f32 v27, v27, v89, v94
	v_fma_f32 v42, v26, v88, v27
	v_fma_f32 v26, v35, v86, v51
	v_fma_f32 v23, v31, v23, v50
	v_fma_f32 v26, v39, v87, v26
	v_fma_f32 v27, v43, v22, v23
	v_mov_b32_e32 v22, v36
	v_mov_b32_e32 v23, v40
	v_fma_f32 v0, v22, v28, v0
	v_fma_f32 v0, v23, v29, v0
	v_mov_b32_e32 v22, v44
	v_mov_b32_e32 v23, v32
	v_mov_b32_e32 v32, v45
	v_fma_f32 v23, v23, v83, v46
	v_fma_f32 v28, v22, v82, v23
	s_nop 0
	v_fma_f32 v22, v37, v84, v47
	v_fma_f32 v29, v41, v85, v22
	v_pk_mul_f32 v[22:23], v[32:33], v[24:25]
	v_mul_f32_e32 v25, 0xbfb8aa3b, v0
	v_exp_f32_e32 v25, v25
	v_mul_f32_e32 v24, 0xbfb8aa3b, v26
	v_exp_f32_e32 v24, v24
	v_add_f32_e32 v23, v23, v48
	v_add_f32_e32 v25, 1.0, v25
	v_rcp_f32_e32 v25, v25
	v_add_f32_e32 v24, 1.0, v24
	v_rcp_f32_e32 v24, v24
	v_add_f32_e32 v22, v22, v23
	v_mul_f32_e32 v0, v0, v25
	v_mul_f32_e32 v25, 0xbfb8aa3b, v29
	v_exp_f32_e32 v25, v25
	v_mul_f32_e32 v24, v26, v24
	v_mul_f32_e32 v26, 0xbfb8aa3b, v42
	v_mul_f32_e32 v23, 0xbfb8aa3b, v34
	v_add_f32_e32 v25, 1.0, v25
	v_rcp_f32_e32 v25, v25
	v_exp_f32_e32 v26, v26
	v_exp_f32_e32 v23, v23
	v_mul_f32_e32 v25, v29, v25
	v_mul_f32_e32 v29, 0xbfb8aa3b, v27
	v_exp_f32_e32 v29, v29
	v_add_f32_e32 v26, 1.0, v26
	v_add_f32_e32 v23, 1.0, v23
	v_rcp_f32_e32 v26, v26
	v_add_f32_e32 v29, 1.0, v29
	v_rcp_f32_e32 v29, v29
	v_rcp_f32_e32 v23, v23
	v_mul_f32_e32 v26, v42, v26
	v_mul_f32_e32 v27, v27, v29
	v_mul_f32_e32 v29, 0xbfb8aa3b, v28
	v_exp_f32_e32 v29, v29
	v_mul_f32_e32 v23, v34, v23
	v_add_f32_e32 v29, 1.0, v29
	v_rcp_f32_e32 v29, v29
	s_nop 0
	v_mul_f32_e32 v28, v28, v29
	v_mul_f32_e32 v29, 0xbfb8aa3b, v22
	v_exp_f32_e32 v29, v29
	s_nop 0
	v_add_f32_e32 v29, 1.0, v29
	v_rcp_f32_e32 v29, v29
	s_nop 0
	v_mul_f32_e32 v29, v22, v29
	v_cvt_pk_bf16_f32 v22, v23, v24
	v_cvt_pk_bf16_f32 v24, v26, v27
	v_lshlrev_b64 v[26:27], 2, v[76:77]
	v_add_u32_e32 v233, 0x8000, v26
	v_cvt_pk_bf16_f32 v23, v0, v25
	v_cvt_pk_bf16_f32 v25, v28, v29
	ds_read_b128 v[28:31], v233 offset:49168
	ds_read_b128 v[40:43], v233 offset:49152
	ds_read_b128 v[44:47], v233 offset:16
	ds_read_b128 v[48:51], v233
	ds_read_b128 v[82:85], v233 offset:12288
	ds_read_b128 v[86:89], v233 offset:12304
	s_waitcnt lgkmcnt(2)
	s_waitcnt lgkmcnt(1)
	v_mov_b32_e32 v33, v82
	v_mov_b32_e32 v82, v49
	v_fma_f32 v0, v48, v18, v40
	v_fma_f32 v40, v33, v19, v0
	s_waitcnt lgkmcnt(0)
	v_mov_b32_e32 v18, v86
	v_mov_b32_e32 v19, v44
	v_mov_b32_e32 v44, v87
	v_fma_f32 v0, v19, v79, v28
	v_fma_f32 v39, v18, v78, v0
	v_fma_f32 v0, v49, v80, v41
	v_fma_f32 v38, v83, v81, v0
	v_fma_f32 v0, v45, v15, v29
	v_fma_f32 v37, v87, v14, v0
	v_mov_b32_e32 v14, v50
	v_mov_b32_e32 v15, v84
	v_mov_b32_e32 v84, v51
	v_fma_f32 v0, v14, v20, v42
	v_fma_f32 v36, v15, v21, v0
	v_mov_b32_e32 v14, v88
	v_mov_b32_e32 v15, v46
	v_mov_b32_e32 v46, v89
	v_fma_f32 v0, v15, v73, v30
	v_fma_f32 v35, v14, v72, v0
	s_nop 0
	v_fma_f32 v0, v51, v74, v43
	v_fma_f32 v34, v85, v75, v0
	v_fma_f32 v0, v47, v17, v31
	s_nop 0
	v_fma_f32 v0, v89, v16, v0
	ds_read_b128 v[18:21], v233 offset:24576
	s_nop 0
	ds_read_b128 v[14:17], v233 offset:24592
	ds_read_b128 v[26:29], v233 offset:36864
	s_nop 0
	ds_read_b128 v[30:33], v233 offset:36880
	s_barrier
	s_waitcnt lgkmcnt(3)
	v_mov_b32_e32 v42, v18
	s_waitcnt lgkmcnt(1)
	v_mov_b32_e32 v43, v26
	v_pk_mul_f32 v[6:7], v[42:43], v[6:7]
	v_mov_b32_e32 v26, v19
	v_add_f32_e32 v6, v40, v6
	v_add_f32_e32 v18, v6, v7
	s_waitcnt lgkmcnt(0)
	v_mov_b32_e32 v6, v30
	v_mov_b32_e32 v7, v14
	v_pk_mul_f32 v[6:7], v[6:7], v[70:71]
	v_mov_b32_e32 v14, v31
	v_add_f32_e32 v7, v7, v39
	v_add_f32_e32 v30, v6, v7
	v_pk_mul_f32 v[6:7], v[26:27], v[68:69]
	v_pk_mul_f32 v[2:3], v[14:15], v[2:3]
	v_add_f32_e32 v6, v38, v6
	v_add_f32_e32 v3, v3, v37
	v_add_f32_e32 v6, v6, v7
	v_add_f32_e32 v7, v2, v3
	v_mov_b32_e32 v2, v20
	v_mov_b32_e32 v3, v28
	v_pk_mul_f32 v[2:3], v[2:3], v[8:9]
	v_mov_b32_e32 v28, v21
	v_add_f32_e32 v2, v36, v2
	v_add_f32_e32 v8, v2, v3
	v_mov_b32_e32 v2, v32
	v_mov_b32_e32 v3, v16
	v_pk_mul_f32 v[2:3], v[2:3], v[66:67]
	v_mov_b32_e32 v16, v33
	v_add_f32_e32 v3, v3, v35
	v_add_f32_e32 v9, v2, v3
	v_pk_mul_f32 v[2:3], v[28:29], v[64:65]
	s_nop 0
	v_add_f32_e32 v2, v34, v2
	v_add_f32_e32 v14, v2, v3
	v_pk_mul_f32 v[2:3], v[16:17], v[4:5]
	v_mul_f32_e32 v4, 0xbfb8aa3b, v8
	v_exp_f32_e32 v4, v4
	v_add_f32_e32 v0, v3, v0
	v_mul_f32_e32 v3, 0xbfb8aa3b, v6
	v_exp_f32_e32 v3, v3
	v_add_f32_e32 v4, 1.0, v4
	v_rcp_f32_e32 v4, v4
	v_add_f32_e32 v0, v2, v0
	v_add_f32_e32 v3, 1.0, v3
	v_rcp_f32_e32 v3, v3
	v_mul_f32_e32 v4, v8, v4
	v_mul_f32_e32 v8, 0xbfb8aa3b, v7
	v_exp_f32_e32 v8, v8
	v_mul_f32_e32 v2, 0xbfb8aa3b, v18
	v_mul_f32_e32 v3, v6, v3
	v_mul_f32_e32 v6, 0xbfb8aa3b, v30
	v_add_f32_e32 v8, 1.0, v8
	v_rcp_f32_e32 v8, v8
	v_exp_f32_e32 v2, v2
	v_mul_f32_e32 v5, 0xbfb8aa3b, v14
	v_exp_f32_e32 v6, v6
	v_mul_f32_e32 v7, v7, v8
	v_mul_f32_e32 v8, 0xbfb8aa3b, v9
	v_exp_f32_e32 v8, v8
	v_exp_f32_e32 v5, v5
	v_add_f32_e32 v2, 1.0, v2
	v_add_f32_e32 v6, 1.0, v6
	v_add_f32_e32 v8, 1.0, v8
	v_rcp_f32_e32 v8, v8
	v_rcp_f32_e32 v2, v2
	v_add_f32_e32 v5, 1.0, v5
	v_rcp_f32_e32 v6, v6
	v_mul_f32_e32 v8, v9, v8
	v_mul_f32_e32 v9, 0xbfb8aa3b, v0
	v_exp_f32_e32 v9, v9
	v_rcp_f32_e32 v5, v5
	v_mul_f32_e32 v2, v18, v2
	v_mul_f32_e32 v6, v30, v6
	v_add_f32_e32 v9, 1.0, v9
	v_rcp_f32_e32 v9, v9
	v_mul_f32_e32 v5, v14, v5
	v_cvt_pk_bf16_f32 v2, v2, v3
	v_cvt_pk_bf16_f32 v3, v4, v5
	v_mul_f32_e32 v0, v0, v9
	v_cvt_pk_bf16_f32 v4, v6, v7
	v_add_u32_e32 v6, s19, v54
	v_cvt_pk_bf16_f32 v5, v8, v0
	v_ashrrev_i32_e32 v7, 31, v6
	v_lshlrev_b32_e32 v0, 1, v56
	s_cbranch_scc1 .LBB0_226
	v_lshlrev_b64 v[8:9], 10, v[6:7]
	v_lshl_add_u64 v[8:9], s[14:15], 0, v[8:9]
	s_add_i32 s88, s22, 0xfffff600
	v_lshl_add_u64 v[8:9], s[88:89], 1, v[8:9]
	v_lshl_add_u64 v[8:9], v[8:9], 0, v[0:1]
	global_store_dwordx4 v[8:9], v[10:13], off
